# same as previous version but 6 (not 10) neighbourhood-attention items per sample-scan workgroup, for more margin on the sample side
# speedup vs baseline: 1.0052x; 1.0019x over previous
; __global__ void __launch_bounds__(NTHREADS, 2) fwd_megakernel(Args args) {
;     ...
;               if (pb < 2 * (256 - NPB)) { scan_item<2>(args, layer, 32 + NPB + (pb >> 1), pb & 1, lds, tid, lane, wave); __syncthreads(); }
;               else { for (int it = pb - 2 * (256 - NPB); it < 1536; it += NPB - 2 * (256 - NPB)) na_item(args, layer, it, lds, tid, lane, wave); } }
.LBB0_446:
	v_readlane_b32 s4, v249, 50
	v_readlane_b32 s5, v249, 51
	s_mov_b64 s[2:3], -1
	s_and_b64 vcc, exec, s[4:5]
	s_barrier
	s_cbranch_vccz .LBB0_466
	v_readlane_b32 s2, v249, 53
	v_writelane_b32 v254, s92, 52
	v_readlane_b32 s3, v249, 54
	s_andn2_b64 vcc, exec, s[2:3]
	v_writelane_b32 v254, s93, 53
	s_cbranch_vccnz .LBB0_465
	v_readlane_b32 s2, v249, 52
	s_nop 1
	v_writelane_b32 v255, s2, 62
	v_readlane_b32 s2, v249, 55
	s_nop 1
	v_writelane_b32 v255, s2, 63
	s_movk_i32 s2, 0x540
	v_writelane_b32 v255, s2, 61

; __global__ void __launch_bounds__(NTHREADS, 2) fwd_megakernel(Args args) {
;     ...
;         if (bid < NSB) {
;             FRESH_TID scan_item<4>(args, layer, bid, 0, lds, tid, lane, wave);
;     ...
;               else { for (int it = pb - 2 * (256 - NPB); it < 1536; it += NPB - 2 * (256 - NPB)) na_item(args, layer, it, lds, tid, lane, wave); } }
.LBB0_662:
	s_waitcnt vmcnt(0) lgkmcnt(0)
	s_barrier
	v_mov_b32_e32 v190, v199
	v_and_b32_e32 v171, 63, v199
	s_add_i32 s4, s68, 0x540
	v_writelane_b32 v255, s4, 62
	s_movk_i32 s4, 32
	v_writelane_b32 v255, s4, 63
	s_movk_i32 s4, 0x600
	v_writelane_b32 v255, s4, 61
	s_mov_b32 s4, 3
	v_writelane_b32 v255, s4, 57
	v_readfirstlane_b32 s26, v190
	s_mov_b32 s93, 0
	s_lshr_b32 s4, s26, 6
	v_writelane_b32 v254, s4, 48
	v_writelane_b32 v254, s92, 52
	v_writelane_b32 v254, s93, 53
	s_branch .Lna_setup
